# weight-conversion loops (phase 0 and the in-proj slack): dropped the loop-top vmcnt(0) that only drained the previous item's stores, so the next item's loads overlap the store drain
# baseline (speedup 1.0000x reference)
.LBB0_197:
	s_cmpk_gt_i32 s14, 0x1ff
	s_mov_b64 s[12:13], -1
	s_cbranch_scc0 .LBB0_211
	s_cmpk_gt_u32 s14, 0x77f
	s_cbranch_scc0 .LBB0_206
	s_cmpk_gt_u32 s14, 0xcff
	s_cbranch_scc0 .LBB0_201
	s_and_b32 s12, s18, 0x1ffc0
	v_or_b32_e32 v34, s12, v32
	s_and_b32 s12, s16, 0x3e0
	v_or_b32_e32 v42, s12, v33
	v_lshlrev_b32_e32 v128, 2, v42
	s_waitcnt lgkmcnt(0)
	v_lshl_add_u64 v[0:1], s[0:1], 0, v[128:129]
	v_lshlrev_b32_e32 v128, 12, v34
	v_lshl_add_u64 v[28:29], v[0:1], 0, v[128:129]
	v_add_co_u32_e32 v4, vcc, 0x1000, v28
	global_load_dwordx4 v[0:3], v[28:29], off nt
	s_nop 0
	v_addc_co_u32_e32 v5, vcc, 0, v29, vcc
	v_add_co_u32_e32 v8, vcc, 0x2000, v28
	v_readlane_b32 s12, v243, 37
	s_nop 0
	v_addc_co_u32_e32 v9, vcc, 0, v29, vcc
	v_add_co_u32_e32 v12, vcc, 0x3000, v28
	v_lshlrev_b32_e32 v128, 1, v34
	s_nop 0
	v_addc_co_u32_e32 v13, vcc, 0, v29, vcc
	v_add_co_u32_e32 v16, vcc, 0x4000, v28
	v_readlane_b32 s13, v243, 38
	s_nop 0
	v_addc_co_u32_e32 v17, vcc, 0, v29, vcc
	v_add_co_u32_e32 v20, vcc, 0x5000, v28
	global_load_dwordx4 v[4:7], v[4:5], off nt
	s_nop 0
	v_addc_co_u32_e32 v21, vcc, 0, v29, vcc
	v_add_co_u32_e32 v24, vcc, 0x6000, v28
	global_load_dwordx4 v[8:11], v[8:9], off nt
	s_nop 0
	v_addc_co_u32_e32 v25, vcc, 0, v29, vcc
	v_add_co_u32_e32 v28, vcc, 0x7000, v28
	global_load_dwordx4 v[12:15], v[12:13], off nt
	s_nop 0
	v_addc_co_u32_e32 v29, vcc, 0, v29, vcc
	global_load_dwordx4 v[16:19], v[16:17], off nt
	v_lshl_add_u64 v[38:39], s[12:13], 0, v[128:129]
	global_load_dwordx4 v[20:23], v[20:21], off nt
	v_mad_u64_u32 v[40:41], s[12:13], v42, s75, v[38:39]
	global_load_dwordx4 v[24:27], v[24:25], off nt
	s_movk_i32 s12, 0x1000
	global_load_dwordx4 v[28:31], v[28:29], off nt
	s_waitcnt vmcnt(0)
	v_cvt_pk_bf16_f32 v34, v0, v4
	v_mul_u32_u24_e32 v0, 0xb00, v42
	v_lshlrev_b32_e32 v128, 1, v0
	v_cvt_pk_bf16_f32 v35, v8, v12
	v_cvt_pk_bf16_f32 v36, v16, v20
	v_cvt_pk_bf16_f32 v37, v24, v28
	global_store_dwordx4 v[40:41], v[34:37], off
	s_nop 1
	v_cvt_pk_bf16_f32 v34, v1, v5
	v_lshl_add_u64 v[4:5], v[38:39], 0, v[128:129]
	v_add_co_u32_e32 v0, vcc, s12, v4
	s_movk_i32 s12, 0x2000
	s_nop 0
	v_addc_co_u32_e32 v1, vcc, 0, v5, vcc
	v_cvt_pk_bf16_f32 v35, v9, v13
	v_cvt_pk_bf16_f32 v36, v17, v21
	v_cvt_pk_bf16_f32 v37, v25, v29
	global_store_dwordx4 v[0:1], v[34:37], off offset:1536
	v_add_co_u32_e32 v0, vcc, s12, v4
	s_nop 0
	v_cvt_pk_bf16_f32 v34, v2, v6
	v_cvt_pk_bf16_f32 v35, v10, v14
	v_cvt_pk_bf16_f32 v36, v18, v22
	v_cvt_pk_bf16_f32 v37, v26, v30
	s_nop 0
	v_addc_co_u32_e32 v1, vcc, 0, v5, vcc
	v_add_co_u32_e32 v4, vcc, 0x4000, v4
	global_store_dwordx4 v[0:1], v[34:37], off offset:3072
	s_nop 0
	v_addc_co_u32_e32 v5, vcc, 0, v5, vcc
	v_cvt_pk_bf16_f32 v0, v3, v7
	v_cvt_pk_bf16_f32 v1, v11, v15
	v_cvt_pk_bf16_f32 v2, v19, v23
	v_cvt_pk_bf16_f32 v3, v27, v31
	global_store_dwordx4 v[4:5], v[0:3], off offset:512
	s_mov_b64 s[12:13], 0
.LBB0_201:
	s_andn2_b64 vcc, exec, s[12:13]
	s_cbranch_vccnz .LBB0_205
	s_add_i32 s12, s14, 0xf880
	s_and_b32 s13, s12, 0xffff
	s_mul_i32 s13, s13, 0xba2f
	s_lshr_b32 s20, s13, 16
	s_lshr_b32 s13, s13, 22
	s_mulk_i32 s13, 0x58
	s_sub_i32 s12, s12, s13
	s_and_b32 s12, s12, 0xffff
	s_and_b32 s13, s20, 0xffc0
	v_or_b32_e32 v35, s13, v32
	v_lshl_or_b32 v34, s12, 5, v33
	v_lshlrev_b32_e32 v128, 2, v34
	v_mul_u32_u24_e32 v4, 0xb00, v35
	s_waitcnt lgkmcnt(0)
	v_lshl_add_u64 v[0:1], s[4:5], 0, v[128:129]
	v_lshlrev_b32_e32 v128, 2, v4
	v_lshl_add_u64 v[24:25], v[0:1], 0, v[128:129]
	s_movk_i32 s13, 0x2000
	v_add_co_u32_e32 v4, vcc, s13, v24
	s_movk_i32 s13, 0x5000
	s_nop 0
	v_addc_co_u32_e32 v5, vcc, 0, v25, vcc
	v_add_co_u32_e32 v8, vcc, s13, v24
	v_mad_u64_u32 v[2:3], s[20:21], v35, s70, v[0:1]
	s_nop 0
	v_addc_co_u32_e32 v9, vcc, 0, v25, vcc
	v_add_co_u32_e32 v12, vcc, 0x8000, v24
	global_load_dwordx4 v[0:3], v[2:3], off nt
	s_nop 0
	global_load_dwordx4 v[4:7], v[4:5], off offset:3072 nt
	v_addc_co_u32_e32 v13, vcc, 0, v25, vcc
	v_add_co_u32_e32 v16, vcc, 0xb000, v24
	global_load_dwordx4 v[8:11], v[8:9], off offset:2048 nt
	s_nop 0
	global_load_dwordx4 v[12:15], v[12:13], off offset:1024 nt
	v_addc_co_u32_e32 v17, vcc, 0, v25, vcc
	v_add_co_u32_e32 v20, vcc, 0xd000, v24
	v_readlane_b32 s20, v243, 51
	s_nop 0
	v_addc_co_u32_e32 v21, vcc, 0, v25, vcc
	v_add_co_u32_e32 v26, vcc, 0x10000, v24
	global_load_dwordx4 v[16:19], v[16:17], off nt
	s_nop 0
	global_load_dwordx4 v[20:23], v[20:21], off offset:3072 nt
	v_addc_co_u32_e32 v27, vcc, 0, v25, vcc
	v_add_co_u32_e32 v28, vcc, 0x13000, v24
	v_readlane_b32 s21, v243, 52
	s_nop 0
	v_addc_co_u32_e32 v29, vcc, 0, v25, vcc
	global_load_dwordx4 v[24:27], v[26:27], off offset:2048 nt
	s_nop 0
	global_load_dwordx4 v[28:31], v[28:29], off offset:1024 nt
	s_andn2_b64 vcc, exec, s[20:21]
	s_cbranch_vccnz .LBB0_204
	v_lshlrev_b32_e32 v40, 2, v35
	global_load_dwordx4 v[36:39], v40, s[6:7]
	s_nop 0
	global_load_dwordx4 v[40:43], v40, s[6:7] offset:16
	s_waitcnt vmcnt(0)
	v_pk_mul_f32 v[2:3], v[2:3], v[36:37] op_sel_hi:[1,0]
	v_pk_mul_f32 v[0:1], v[0:1], v[36:37] op_sel_hi:[1,0]
	v_pk_mul_f32 v[6:7], v[6:7], v[36:37] op_sel:[0,1]
	v_pk_mul_f32 v[4:5], v[4:5], v[36:37] op_sel:[0,1]
	v_pk_mul_f32 v[10:11], v[10:11], v[38:39] op_sel_hi:[1,0]
	v_pk_mul_f32 v[8:9], v[8:9], v[38:39] op_sel_hi:[1,0]
	v_mov_b32_e32 v36, v39
	v_mov_b32_e32 v38, v43
	v_pk_mul_f32 v[18:19], v[18:19], v[40:41] op_sel_hi:[1,0]
	v_pk_mul_f32 v[16:17], v[16:17], v[40:41] op_sel_hi:[1,0]
	v_pk_mul_f32 v[22:23], v[22:23], v[40:41] op_sel:[0,1]
	v_pk_mul_f32 v[20:21], v[20:21], v[40:41] op_sel:[0,1]
	v_pk_mul_f32 v[26:27], v[26:27], v[42:43] op_sel_hi:[1,0]
	v_pk_mul_f32 v[24:25], v[24:25], v[42:43] op_sel_hi:[1,0]
	v_pk_mul_f32 v[14:15], v[14:15], v[36:37] op_sel_hi:[1,0]
	v_pk_mul_f32 v[12:13], v[12:13], v[36:37] op_sel_hi:[1,0]
	v_pk_mul_f32 v[30:31], v[30:31], v[38:39] op_sel_hi:[1,0]
	v_pk_mul_f32 v[28:29], v[28:29], v[38:39] op_sel_hi:[1,0]

.LBB0_206:
	s_andn2_b64 vcc, exec, s[12:13]
	s_cbranch_vccnz .LBB0_210
	s_add_i32 s12, s14, 0xfe00
	s_and_b32 s13, s12, 0xffff
	s_mul_i32 s13, s13, 0xba2f
	s_lshr_b32 s20, s13, 16
	s_lshr_b32 s13, s13, 22
	s_mulk_i32 s13, 0x58
	s_sub_i32 s12, s12, s13
	s_and_b32 s12, s12, 0xffff
	s_and_b32 s13, s20, 0xffc0
	v_or_b32_e32 v35, s13, v32
	v_lshl_or_b32 v34, s12, 5, v33
	v_lshlrev_b32_e32 v128, 2, v34
	v_mul_u32_u24_e32 v4, 0xb00, v35
	s_waitcnt lgkmcnt(0)
	v_lshl_add_u64 v[0:1], s[8:9], 0, v[128:129]
	v_lshlrev_b32_e32 v128, 2, v4
	v_lshl_add_u64 v[24:25], v[0:1], 0, v[128:129]
	s_movk_i32 s13, 0x2000
	v_add_co_u32_e32 v4, vcc, s13, v24
	s_movk_i32 s13, 0x5000
	s_nop 0
	v_addc_co_u32_e32 v5, vcc, 0, v25, vcc
	v_add_co_u32_e32 v8, vcc, s13, v24
	v_mad_u64_u32 v[2:3], s[20:21], v35, s70, v[0:1]
	s_nop 0
	v_addc_co_u32_e32 v9, vcc, 0, v25, vcc
	v_add_co_u32_e32 v12, vcc, 0x8000, v24
	global_load_dwordx4 v[0:3], v[2:3], off nt
	s_nop 0
	global_load_dwordx4 v[4:7], v[4:5], off offset:3072 nt
	v_addc_co_u32_e32 v13, vcc, 0, v25, vcc
	v_add_co_u32_e32 v16, vcc, 0xb000, v24
	global_load_dwordx4 v[8:11], v[8:9], off offset:2048 nt
	s_nop 0
	global_load_dwordx4 v[12:15], v[12:13], off offset:1024 nt
	v_addc_co_u32_e32 v17, vcc, 0, v25, vcc
	v_add_co_u32_e32 v20, vcc, 0xd000, v24
	v_readlane_b32 s20, v243, 51
	s_nop 0
	v_addc_co_u32_e32 v21, vcc, 0, v25, vcc
	v_add_co_u32_e32 v26, vcc, 0x10000, v24
	global_load_dwordx4 v[16:19], v[16:17], off nt
	s_nop 0
	global_load_dwordx4 v[20:23], v[20:21], off offset:3072 nt
	v_addc_co_u32_e32 v27, vcc, 0, v25, vcc
	v_add_co_u32_e32 v28, vcc, 0x13000, v24
	v_readlane_b32 s21, v243, 52
	s_nop 0
	v_addc_co_u32_e32 v29, vcc, 0, v25, vcc
	global_load_dwordx4 v[24:27], v[26:27], off offset:2048 nt
	s_nop 0
	global_load_dwordx4 v[28:31], v[28:29], off offset:1024 nt
	s_andn2_b64 vcc, exec, s[20:21]
	s_cbranch_vccnz .LBB0_209
	v_lshlrev_b32_e32 v40, 2, v35
	global_load_dwordx4 v[36:39], v40, s[6:7]
	s_nop 0
	global_load_dwordx4 v[40:43], v40, s[6:7] offset:16
	s_waitcnt vmcnt(0)
	v_pk_mul_f32 v[2:3], v[2:3], v[36:37] op_sel_hi:[1,0]
	v_pk_mul_f32 v[0:1], v[0:1], v[36:37] op_sel_hi:[1,0]
	v_pk_mul_f32 v[6:7], v[6:7], v[36:37] op_sel:[0,1]
	v_pk_mul_f32 v[4:5], v[4:5], v[36:37] op_sel:[0,1]
	v_pk_mul_f32 v[10:11], v[10:11], v[38:39] op_sel_hi:[1,0]
	v_pk_mul_f32 v[8:9], v[8:9], v[38:39] op_sel_hi:[1,0]
	v_mov_b32_e32 v36, v39
	v_mov_b32_e32 v38, v43
	v_pk_mul_f32 v[18:19], v[18:19], v[40:41] op_sel_hi:[1,0]
	v_pk_mul_f32 v[16:17], v[16:17], v[40:41] op_sel_hi:[1,0]
	v_pk_mul_f32 v[22:23], v[22:23], v[40:41] op_sel:[0,1]
	v_pk_mul_f32 v[20:21], v[20:21], v[40:41] op_sel:[0,1]
	v_pk_mul_f32 v[26:27], v[26:27], v[42:43] op_sel_hi:[1,0]
	v_pk_mul_f32 v[24:25], v[24:25], v[42:43] op_sel_hi:[1,0]
	v_pk_mul_f32 v[14:15], v[14:15], v[36:37] op_sel_hi:[1,0]
	v_pk_mul_f32 v[12:13], v[12:13], v[36:37] op_sel_hi:[1,0]
	v_pk_mul_f32 v[30:31], v[30:31], v[38:39] op_sel_hi:[1,0]
	v_pk_mul_f32 v[28:29], v[28:29], v[38:39] op_sel_hi:[1,0]

.LBB0_211:
	s_andn2_b64 vcc, exec, s[12:13]
	s_cbranch_vccnz .LBB0_196
	s_ashr_i32 s12, s14, 31
	s_lshr_b32 s12, s12, 27
	s_add_i32 s12, s14, s12
	s_ashr_i32 s12, s12, 5
	v_lshl_or_b32 v0, s12, 6, v32
	s_waitcnt lgkmcnt(0)
	v_add_u32_e32 v1, s16, v33
	s_lshl_b32 s12, s12, 10
	v_subrev_u32_e32 v30, s12, v1
	v_ashrrev_i32_e32 v31, 31, v30
	v_ashrrev_i32_e32 v1, 31, v0
	v_or_b32_e32 v6, 1, v0
	v_or_b32_e32 v10, 2, v0
	v_or_b32_e32 v14, 3, v0
	v_or_b32_e32 v18, 4, v0
	v_or_b32_e32 v22, 5, v0
	v_or_b32_e32 v26, 6, v0
	v_or_b32_e32 v36, 7, v0
	v_lshl_add_u64 v[34:35], v[30:31], 2, s[10:11]
	v_lshlrev_b64 v[2:3], 12, v[0:1]
	v_ashrrev_i32_e32 v7, 31, v6
	v_ashrrev_i32_e32 v11, 31, v10
	v_ashrrev_i32_e32 v15, 31, v14
	v_ashrrev_i32_e32 v19, 31, v18
	v_ashrrev_i32_e32 v23, 31, v22
	v_ashrrev_i32_e32 v27, 31, v26
	v_ashrrev_i32_e32 v37, 31, v36
	v_readlane_b32 s12, v243, 41
	v_lshl_add_u64 v[2:3], v[34:35], 0, v[2:3]
	v_lshlrev_b64 v[6:7], 12, v[6:7]
	v_lshlrev_b64 v[10:11], 12, v[10:11]
	v_lshlrev_b64 v[14:15], 12, v[14:15]
	v_lshlrev_b64 v[18:19], 12, v[18:19]
	v_lshlrev_b64 v[22:23], 12, v[22:23]
	v_lshlrev_b64 v[26:27], 12, v[26:27]
	v_lshlrev_b64 v[36:37], 12, v[36:37]
	v_readlane_b32 s13, v243, 42
	global_load_dwordx4 v[2:5], v[2:3], off nt
	v_lshl_add_u64 v[6:7], v[34:35], 0, v[6:7]
	v_lshl_add_u64 v[10:11], v[34:35], 0, v[10:11]
	v_lshl_add_u64 v[14:15], v[34:35], 0, v[14:15]
	v_lshl_add_u64 v[18:19], v[34:35], 0, v[18:19]
	v_lshl_add_u64 v[22:23], v[34:35], 0, v[22:23]
	v_lshl_add_u64 v[26:27], v[34:35], 0, v[26:27]
	v_lshl_add_u64 v[34:35], v[34:35], 0, v[36:37]
	v_lshl_add_u64 v[0:1], v[0:1], 1, s[12:13]
	v_lshlrev_b64 v[42:43], 11, v[30:31]
	global_load_dwordx4 v[6:9], v[6:7], off nt
	v_lshl_add_u64 v[42:43], v[0:1], 0, v[42:43]
	global_load_dwordx4 v[10:13], v[10:11], off nt
	s_nop 0
	global_load_dwordx4 v[14:17], v[14:15], off nt
	s_nop 0
	global_load_dwordx4 v[18:21], v[18:19], off nt
	s_nop 0
	global_load_dwordx4 v[22:25], v[22:23], off nt
	s_nop 0
	global_load_dwordx4 v[26:29], v[26:27], off nt
	s_nop 0
	global_load_dwordx4 v[34:37], v[34:35], off nt
	s_waitcnt vmcnt(0)
	v_cvt_pk_bf16_f32 v38, v2, v6
	v_add_u32_e32 v2, 1, v30
	v_cvt_pk_bf16_f32 v39, v10, v14
	v_cvt_pk_bf16_f32 v40, v18, v22
	v_cvt_pk_bf16_f32 v41, v26, v34
	global_store_dwordx4 v[42:43], v[38:41], off
	v_add_u32_e32 v6, 3, v30
	s_nop 0
	v_cvt_pk_bf16_f32 v38, v3, v7
	v_ashrrev_i32_e32 v3, 31, v2
	v_lshlrev_b64 v[2:3], 11, v[2:3]
	v_lshl_add_u64 v[2:3], v[0:1], 0, v[2:3]
	v_cvt_pk_bf16_f32 v39, v11, v15
	v_cvt_pk_bf16_f32 v40, v19, v23
	v_cvt_pk_bf16_f32 v41, v27, v35
	global_store_dwordx4 v[2:3], v[38:41], off
	v_add_u32_e32 v2, 2, v30
	v_ashrrev_i32_e32 v3, 31, v2
	v_ashrrev_i32_e32 v7, 31, v6
	v_lshlrev_b64 v[2:3], 11, v[2:3]
	v_lshlrev_b64 v[6:7], 11, v[6:7]
	v_lshl_add_u64 v[2:3], v[0:1], 0, v[2:3]
	v_lshl_add_u64 v[0:1], v[0:1], 0, v[6:7]
	v_cvt_pk_bf16_f32 v38, v4, v8
	v_cvt_pk_bf16_f32 v39, v12, v16
	v_cvt_pk_bf16_f32 v40, v20, v24
	v_cvt_pk_bf16_f32 v41, v28, v36
	global_store_dwordx4 v[2:3], v[38:41], off
	v_cvt_pk_bf16_f32 v2, v5, v9
	v_cvt_pk_bf16_f32 v3, v13, v17
	v_cvt_pk_bf16_f32 v4, v21, v25
	v_cvt_pk_bf16_f32 v5, v29, v37
	global_store_dwordx4 v[0:1], v[2:5], off
	s_branch .LBB0_196

.LBB0_374:
	s_cmpk_gt_i32 s2, 0x57f
	s_mov_b64 s[0:1], -1
	s_cbranch_scc0 .LBB0_388
	s_cmpk_gt_u32 s2, 0xaff
	s_cbranch_scc0 .LBB0_383
	s_cmpk_gt_u32 s2, 0x107f
	s_cbranch_scc0 .LBB0_380
	s_add_i32 s0, s2, 0xef80
	s_and_b32 s1, s0, 0xffff
	s_mul_i32 s1, s1, 0x8889
	s_lshr_b32 s9, s1, 16
	s_lshr_b32 s1, s1, 22
	s_mulk_i32 s1, 0x78
	s_sub_i32 s0, s0, s1
	s_lshl_b32 s0, s0, 5
	s_and_b32 s0, s0, 0xffe0
	s_and_b32 s1, s9, 0xffc0
	v_or_b32_e32 v32, s0, v37
	v_readlane_b32 s36, v243, 62
	v_or_b32_e32 v33, s1, v36
	v_lshlrev_b32_e32 v128, 2, v32
	v_readlane_b32 s48, v242, 10
	v_readlane_b32 s49, v242, 11
	s_movk_i32 s0, 0x3c00
	v_mul_u32_u24_e32 v4, 0xf00, v33
	s_waitcnt lgkmcnt(0)
	v_lshl_add_u64 v[0:1], s[48:49], 0, v[128:129]
	v_mad_u64_u32 v[2:3], s[0:1], v33, s0, v[0:1]
	v_lshlrev_b32_e32 v128, 2, v4
	v_lshl_add_u64 v[24:25], v[0:1], 0, v[128:129]
	s_movk_i32 s0, 0x3000
	v_add_co_u32_e32 v4, vcc, s0, v24
	s_movk_i32 s0, 0x7000
	s_nop 0
	v_addc_co_u32_e32 v5, vcc, 0, v25, vcc
	v_add_co_u32_e32 v8, vcc, s0, v24
	global_load_dwordx4 v[0:3], v[2:3], off nt
	s_nop 0
	global_load_dwordx4 v[4:7], v[4:5], off offset:3072 nt
	v_addc_co_u32_e32 v9, vcc, 0, v25, vcc
	v_add_co_u32_e32 v12, vcc, 0xb000, v24
	v_readlane_b32 s0, v243, 57
	s_nop 0
	v_addc_co_u32_e32 v13, vcc, 0, v25, vcc
	v_add_co_u32_e32 v16, vcc, 0xf000, v24
	global_load_dwordx4 v[8:11], v[8:9], off offset:2048 nt
	s_nop 0
	global_load_dwordx4 v[12:15], v[12:13], off offset:1024 nt
	v_addc_co_u32_e32 v17, vcc, 0, v25, vcc
	v_add_co_u32_e32 v20, vcc, 0x12000, v24
	v_readlane_b32 s1, v243, 58
	s_nop 0
	v_addc_co_u32_e32 v21, vcc, 0, v25, vcc
	v_add_co_u32_e32 v26, vcc, 0x16000, v24
	global_load_dwordx4 v[16:19], v[16:17], off nt
	s_nop 0
	global_load_dwordx4 v[20:23], v[20:21], off offset:3072 nt
	v_addc_co_u32_e32 v27, vcc, 0, v25, vcc
	v_add_co_u32_e32 v28, vcc, 0x1a000, v24
	v_readlane_b32 s46, v242, 8
	s_nop 0
	v_addc_co_u32_e32 v29, vcc, 0, v25, vcc
	global_load_dwordx4 v[24:27], v[26:27], off offset:2048 nt
	s_nop 0
	global_load_dwordx4 v[28:31], v[28:29], off offset:1024 nt
	v_readlane_b32 s47, v242, 9
	s_andn2_b64 vcc, exec, s[0:1]
	v_readlane_b32 s37, v243, 63
	v_readlane_b32 s38, v242, 0
	v_readlane_b32 s39, v242, 1
	v_readlane_b32 s40, v242, 2
	v_readlane_b32 s41, v242, 3
	v_readlane_b32 s42, v242, 4
	v_readlane_b32 s43, v242, 5
	v_readlane_b32 s44, v242, 6
	v_readlane_b32 s45, v242, 7
	v_readlane_b32 s50, v242, 12
	v_readlane_b32 s51, v242, 13
	s_cbranch_vccnz .LBB0_379
	v_lshlrev_b32_e32 v34, 2, v33
	global_load_dwordx4 v[38:41], v34, s[46:47]
	global_load_dwordx4 v[42:45], v34, s[46:47] offset:16
	s_waitcnt vmcnt(1)
	v_pk_mul_f32 v[2:3], v[2:3], v[38:39] op_sel_hi:[1,0]
	v_pk_mul_f32 v[0:1], v[0:1], v[38:39] op_sel_hi:[1,0]
	v_pk_mul_f32 v[6:7], v[6:7], v[38:39] op_sel:[0,1]
	v_pk_mul_f32 v[4:5], v[4:5], v[38:39] op_sel:[0,1]
	v_mov_b32_e32 v34, v41
	s_waitcnt vmcnt(0)
	v_mov_b32_e32 v38, v45
	v_pk_mul_f32 v[18:19], v[18:19], v[42:43] op_sel_hi:[1,0]
	v_pk_mul_f32 v[16:17], v[16:17], v[42:43] op_sel_hi:[1,0]
	v_pk_mul_f32 v[22:23], v[22:23], v[42:43] op_sel:[0,1]
	v_pk_mul_f32 v[20:21], v[20:21], v[42:43] op_sel:[0,1]
	v_pk_mul_f32 v[10:11], v[10:11], v[40:41] op_sel_hi:[1,0]
	v_pk_mul_f32 v[8:9], v[8:9], v[40:41] op_sel_hi:[1,0]
	v_pk_mul_f32 v[26:27], v[26:27], v[44:45] op_sel_hi:[1,0]
	v_pk_mul_f32 v[24:25], v[24:25], v[44:45] op_sel_hi:[1,0]
	v_pk_mul_f32 v[14:15], v[14:15], v[34:35] op_sel_hi:[1,0]
	v_pk_mul_f32 v[12:13], v[12:13], v[34:35] op_sel_hi:[1,0]
	v_pk_mul_f32 v[30:31], v[30:31], v[38:39] op_sel_hi:[1,0]
	v_pk_mul_f32 v[28:29], v[28:29], v[38:39] op_sel_hi:[1,0]

.LBB0_380:
	s_and_b64 vcc, exec, s[0:1]
	s_cbranch_vccz .LBB0_382
	s_and_b32 s0, s7, 0x1ffc0
	v_or_b32_e32 v32, s0, v36
	s_and_b32 s0, s3, 0x3e0
	v_or_b32_e32 v34, s0, v37
	v_readlane_b32 s36, v243, 62
	v_lshlrev_b32_e32 v128, 2, v34
	v_readlane_b32 s44, v242, 6
	v_readlane_b32 s45, v242, 7
	v_readlane_b32 s0, v243, 55
	v_readlane_b32 s1, v243, 56
	s_waitcnt lgkmcnt(0)
	v_lshl_add_u64 v[0:1], s[44:45], 0, v[128:129]
	v_lshlrev_b32_e32 v128, 12, v32
	v_lshl_add_u64 v[24:25], v[0:1], 0, v[128:129]
	v_add_co_u32_e32 v4, vcc, 0x1000, v24
	v_lshlrev_b32_e32 v128, 1, v32
	s_nop 0
	v_addc_co_u32_e32 v5, vcc, 0, v25, vcc
	v_add_co_u32_e32 v8, vcc, 0x2000, v24
	global_load_dwordx4 v[0:3], v[24:25], off nt
	s_nop 0
	global_load_dwordx4 v[4:7], v[4:5], off nt
	v_addc_co_u32_e32 v9, vcc, 0, v25, vcc
	v_add_co_u32_e32 v12, vcc, 0x3000, v24
	v_mul_u32_u24_e32 v35, 0xb00, v34
	s_nop 0
	v_addc_co_u32_e32 v13, vcc, 0, v25, vcc
	v_add_co_u32_e32 v16, vcc, 0x4000, v24
	global_load_dwordx4 v[8:11], v[8:9], off nt
	s_nop 0
	global_load_dwordx4 v[12:15], v[12:13], off nt
	v_addc_co_u32_e32 v17, vcc, 0, v25, vcc
	v_add_co_u32_e32 v20, vcc, 0x5000, v24
	v_lshl_add_u64 v[32:33], s[0:1], 0, v[128:129]
	s_nop 0
	v_addc_co_u32_e32 v21, vcc, 0, v25, vcc
	v_add_co_u32_e32 v26, vcc, 0x6000, v24
	global_load_dwordx4 v[16:19], v[16:17], off nt
	s_nop 0
	global_load_dwordx4 v[20:23], v[20:21], off nt
	v_addc_co_u32_e32 v27, vcc, 0, v25, vcc
	v_add_co_u32_e32 v28, vcc, 0x7000, v24
	v_lshlrev_b32_e32 v128, 1, v35
	s_nop 0
	v_addc_co_u32_e32 v29, vcc, 0, v25, vcc
	global_load_dwordx4 v[24:27], v[26:27], off nt
	s_nop 0
	global_load_dwordx4 v[28:31], v[28:29], off nt
	v_mad_u64_u32 v[38:39], s[0:1], v34, s75, v[32:33]
	v_lshl_add_u64 v[40:41], v[32:33], 0, v[128:129]
	s_movk_i32 s0, 0x1000
	v_add_co_u32_e32 v42, vcc, s0, v40
	s_movk_i32 s0, 0x2000
	s_nop 0
	v_addc_co_u32_e32 v43, vcc, 0, v41, vcc
	v_add_co_u32_e32 v44, vcc, s0, v40
	v_readlane_b32 s37, v243, 63
	s_nop 0
	v_addc_co_u32_e32 v45, vcc, 0, v41, vcc
	v_add_co_u32_e32 v40, vcc, 0x4000, v40
	v_readlane_b32 s38, v242, 0
	s_nop 0
	v_addc_co_u32_e32 v41, vcc, 0, v41, vcc
	v_readlane_b32 s39, v242, 1
	v_readlane_b32 s40, v242, 2
	v_readlane_b32 s41, v242, 3
	v_readlane_b32 s42, v242, 4
	v_readlane_b32 s43, v242, 5
	v_readlane_b32 s46, v242, 8
	v_readlane_b32 s47, v242, 9
	v_readlane_b32 s48, v242, 10
	v_readlane_b32 s49, v242, 11
	v_readlane_b32 s50, v242, 12
	v_readlane_b32 s51, v242, 13
	s_waitcnt vmcnt(6)
	v_cvt_pk_bf16_f32 v32, v0, v4
	s_waitcnt vmcnt(4)
	v_cvt_pk_bf16_f32 v33, v8, v12
	s_waitcnt vmcnt(2)
	v_cvt_pk_bf16_f32 v34, v16, v20
	s_waitcnt vmcnt(0)
	v_cvt_pk_bf16_f32 v35, v24, v28
	global_store_dwordx4 v[38:39], v[32:35], off
	s_nop 1
	v_cvt_pk_bf16_f32 v32, v1, v5
	v_cvt_pk_bf16_f32 v33, v9, v13
	v_cvt_pk_bf16_f32 v34, v17, v21
	v_cvt_pk_bf16_f32 v35, v25, v29
	global_store_dwordx4 v[42:43], v[32:35], off offset:1536
	s_nop 1
	v_cvt_pk_bf16_f32 v32, v2, v6
	v_cvt_pk_bf16_f32 v33, v10, v14
	v_cvt_pk_bf16_f32 v34, v18, v22
	v_cvt_pk_bf16_f32 v35, v26, v30
	global_store_dwordx4 v[44:45], v[32:35], off offset:3072
	v_cvt_pk_bf16_f32 v0, v3, v7
	v_cvt_pk_bf16_f32 v1, v11, v15
	v_cvt_pk_bf16_f32 v2, v19, v23
	v_cvt_pk_bf16_f32 v3, v27, v31
	global_store_dwordx4 v[40:41], v[0:3], off offset:512

.LBB0_383:
	s_andn2_b64 vcc, exec, s[0:1]
	s_cbranch_vccnz .LBB0_387
	s_add_i32 s0, s2, 0xfa80
	s_and_b32 s1, s0, 0xffff
	s_mul_i32 s1, s1, 0xba2f
	s_lshr_b32 s9, s1, 16
	s_lshr_b32 s1, s1, 22
	s_mulk_i32 s1, 0x58
	s_sub_i32 s0, s0, s1
	s_and_b32 s0, s0, 0xffff
	s_and_b32 s1, s9, 0xffc0
	v_or_b32_e32 v33, s1, v36
	v_lshl_or_b32 v32, s0, 5, v37
	v_readlane_b32 s36, v243, 62
	v_lshlrev_b32_e32 v128, 2, v32
	v_readlane_b32 s42, v242, 4
	v_readlane_b32 s43, v242, 5
	v_mul_u32_u24_e32 v4, 0xb00, v33
	s_movk_i32 s1, 0x2000
	s_waitcnt lgkmcnt(0)
	v_lshl_add_u64 v[0:1], s[42:43], 0, v[128:129]
	v_lshlrev_b32_e32 v128, 2, v4
	v_lshl_add_u64 v[24:25], v[0:1], 0, v[128:129]
	v_add_co_u32_e32 v4, vcc, s1, v24
	s_movk_i32 s1, 0x5000
	s_nop 0
	v_addc_co_u32_e32 v5, vcc, 0, v25, vcc
	v_add_co_u32_e32 v8, vcc, s1, v24
	v_mad_u64_u32 v[2:3], s[10:11], v33, s70, v[0:1]
	s_nop 0
	v_addc_co_u32_e32 v9, vcc, 0, v25, vcc
	v_add_co_u32_e32 v12, vcc, 0x8000, v24
	global_load_dwordx4 v[0:3], v[2:3], off nt
	s_nop 0
	global_load_dwordx4 v[4:7], v[4:5], off offset:3072 nt
	v_addc_co_u32_e32 v13, vcc, 0, v25, vcc
	v_add_co_u32_e32 v16, vcc, 0xb000, v24
	global_load_dwordx4 v[8:11], v[8:9], off offset:2048 nt
	s_nop 0
	global_load_dwordx4 v[12:15], v[12:13], off offset:1024 nt
	v_addc_co_u32_e32 v17, vcc, 0, v25, vcc
	v_add_co_u32_e32 v20, vcc, 0xd000, v24
	v_readlane_b32 s38, v242, 0
	s_nop 0
	v_addc_co_u32_e32 v21, vcc, 0, v25, vcc
	v_add_co_u32_e32 v26, vcc, 0x10000, v24
	global_load_dwordx4 v[16:19], v[16:17], off nt
	s_nop 0
	global_load_dwordx4 v[20:23], v[20:21], off offset:3072 nt
	v_addc_co_u32_e32 v27, vcc, 0, v25, vcc
	v_add_co_u32_e32 v28, vcc, 0x13000, v24
	v_readlane_b32 s39, v242, 1
	s_nop 0
	v_addc_co_u32_e32 v29, vcc, 0, v25, vcc
	global_load_dwordx4 v[24:27], v[26:27], off offset:2048 nt
	s_nop 0
	global_load_dwordx4 v[28:31], v[28:29], off offset:1024 nt
	s_andn2_b64 vcc, exec, s[20:21]
	v_readlane_b32 s37, v243, 63
	v_readlane_b32 s40, v242, 2
	v_readlane_b32 s41, v242, 3
	v_readlane_b32 s44, v242, 6
	v_readlane_b32 s45, v242, 7
	v_readlane_b32 s46, v242, 8
	v_readlane_b32 s47, v242, 9
	v_readlane_b32 s48, v242, 10
	v_readlane_b32 s49, v242, 11
	v_readlane_b32 s50, v242, 12
	v_readlane_b32 s51, v242, 13
	s_cbranch_vccnz .LBB0_386
	v_lshlrev_b32_e32 v34, 2, v33
	global_load_dwordx4 v[38:41], v34, s[38:39]
	global_load_dwordx4 v[42:45], v34, s[38:39] offset:16
	s_waitcnt vmcnt(1)
	v_pk_mul_f32 v[2:3], v[2:3], v[38:39] op_sel_hi:[1,0]
	v_pk_mul_f32 v[0:1], v[0:1], v[38:39] op_sel_hi:[1,0]
	v_pk_mul_f32 v[6:7], v[6:7], v[38:39] op_sel:[0,1]
	v_pk_mul_f32 v[4:5], v[4:5], v[38:39] op_sel:[0,1]
	v_mov_b32_e32 v34, v41
	s_waitcnt vmcnt(0)
	v_mov_b32_e32 v38, v45
	v_pk_mul_f32 v[18:19], v[18:19], v[42:43] op_sel_hi:[1,0]
	v_pk_mul_f32 v[16:17], v[16:17], v[42:43] op_sel_hi:[1,0]
	v_pk_mul_f32 v[22:23], v[22:23], v[42:43] op_sel:[0,1]
	v_pk_mul_f32 v[20:21], v[20:21], v[42:43] op_sel:[0,1]
	v_pk_mul_f32 v[10:11], v[10:11], v[40:41] op_sel_hi:[1,0]
	v_pk_mul_f32 v[8:9], v[8:9], v[40:41] op_sel_hi:[1,0]
	v_pk_mul_f32 v[26:27], v[26:27], v[44:45] op_sel_hi:[1,0]
	v_pk_mul_f32 v[24:25], v[24:25], v[44:45] op_sel_hi:[1,0]
	v_pk_mul_f32 v[14:15], v[14:15], v[34:35] op_sel_hi:[1,0]
	v_pk_mul_f32 v[12:13], v[12:13], v[34:35] op_sel_hi:[1,0]
	v_pk_mul_f32 v[30:31], v[30:31], v[38:39] op_sel_hi:[1,0]
	v_pk_mul_f32 v[28:29], v[28:29], v[38:39] op_sel_hi:[1,0]

.LBB0_388:
	s_andn2_b64 vcc, exec, s[0:1]
	s_cbranch_vccnz .LBB0_373
	s_mul_hi_i32 s0, s2, 0x2e8ba2e9
	s_lshr_b32 s1, s0, 31
	s_ashr_i32 s0, s0, 4
	s_add_i32 s0, s0, s1
	s_mul_i32 s1, s0, 0xfffff500
	s_add_i32 s1, s1, s3
	v_add_u32_e32 v34, s1, v37
	v_readlane_b32 s36, v243, 62
	v_lshl_or_b32 v32, s0, 6, v36
	v_ashrrev_i32_e32 v35, 31, v34
	v_readlane_b32 s40, v242, 2
	v_readlane_b32 s41, v242, 3
	v_or_b32_e32 v2, 1, v32
	v_or_b32_e32 v8, 2, v32
	v_lshl_add_u64 v[24:25], v[34:35], 2, s[40:41]
	v_or_b32_e32 v10, 3, v32
	v_or_b32_e32 v16, 4, v32
	v_or_b32_e32 v18, 5, v32
	v_or_b32_e32 v26, 6, v32
	v_or_b32_e32 v28, 7, v32
	s_waitcnt lgkmcnt(0)
	v_mad_i64_i32 v[0:1], s[10:11], v32, s70, v[24:25]
	v_mad_i64_i32 v[4:5], s[10:11], v2, s70, v[24:25]
	v_mad_i64_i32 v[8:9], s[10:11], v8, s70, v[24:25]
	v_mad_i64_i32 v[12:13], s[10:11], v10, s70, v[24:25]
	v_mad_i64_i32 v[16:17], s[10:11], v16, s70, v[24:25]
	v_mad_i64_i32 v[20:21], s[10:11], v18, s70, v[24:25]
	v_mad_i64_i32 v[26:27], s[10:11], v26, s70, v[24:25]
	v_mad_i64_i32 v[28:29], s[10:11], v28, s70, v[24:25]
	global_load_dwordx4 v[0:3], v[0:1], off nt
	s_nop 0
	global_load_dwordx4 v[4:7], v[4:5], off nt
	s_nop 0
	global_load_dwordx4 v[8:11], v[8:9], off nt
	s_nop 0
	global_load_dwordx4 v[12:15], v[12:13], off nt
	s_nop 0
	global_load_dwordx4 v[16:19], v[16:17], off nt
	s_nop 0
	global_load_dwordx4 v[20:23], v[20:21], off nt
	s_nop 0
	global_load_dwordx4 v[24:27], v[26:27], off nt
	s_nop 0
	global_load_dwordx4 v[28:31], v[28:29], off nt
	v_readlane_b32 s38, v242, 0
	v_readlane_b32 s39, v242, 1
	s_andn2_b64 vcc, exec, s[20:21]
	v_ashrrev_i32_e32 v33, 31, v32
	v_readlane_b32 s37, v243, 63
	v_readlane_b32 s42, v242, 4
	v_readlane_b32 s43, v242, 5
	v_readlane_b32 s44, v242, 6
	v_readlane_b32 s45, v242, 7
	v_readlane_b32 s46, v242, 8
	v_readlane_b32 s47, v242, 9
	v_readlane_b32 s48, v242, 10
	v_readlane_b32 s49, v242, 11
	v_readlane_b32 s50, v242, 12
	v_readlane_b32 s51, v242, 13
	s_cbranch_vccnz .LBB0_372
	v_lshl_add_u64 v[42:43], v[32:33], 2, s[38:39]
	global_load_dwordx4 v[38:41], v[42:43], off
	s_nop 0
	global_load_dwordx4 v[42:45], v[42:43], off offset:16
	s_waitcnt vmcnt(1)
	v_pk_mul_f32 v[2:3], v[2:3], v[38:39] op_sel_hi:[1,0]
	v_pk_mul_f32 v[0:1], v[0:1], v[38:39] op_sel_hi:[1,0]
	v_pk_mul_f32 v[6:7], v[6:7], v[38:39] op_sel:[0,1]
	v_pk_mul_f32 v[4:5], v[4:5], v[38:39] op_sel:[0,1]
	v_pk_mul_f32 v[10:11], v[10:11], v[40:41] op_sel_hi:[1,0]
	v_pk_mul_f32 v[8:9], v[8:9], v[40:41] op_sel_hi:[1,0]
	v_mov_b32_e32 v38, v41
	s_waitcnt vmcnt(0)
	v_mov_b32_e32 v40, v45
	v_pk_mul_f32 v[18:19], v[18:19], v[42:43] op_sel_hi:[1,0]
	v_pk_mul_f32 v[16:17], v[16:17], v[42:43] op_sel_hi:[1,0]
	v_pk_mul_f32 v[22:23], v[22:23], v[42:43] op_sel:[0,1]
	v_pk_mul_f32 v[20:21], v[20:21], v[42:43] op_sel:[0,1]
	v_pk_mul_f32 v[26:27], v[26:27], v[44:45] op_sel_hi:[1,0]
	v_pk_mul_f32 v[24:25], v[24:25], v[44:45] op_sel_hi:[1,0]
	v_pk_mul_f32 v[14:15], v[14:15], v[38:39] op_sel_hi:[1,0]
	v_pk_mul_f32 v[12:13], v[12:13], v[38:39] op_sel_hi:[1,0]
	v_pk_mul_f32 v[30:31], v[30:31], v[40:41] op_sel_hi:[1,0]
	v_pk_mul_f32 v[28:29], v[28:29], v[40:41] op_sel_hi:[1,0]
	s_branch .LBB0_372
